# G5 (down GEMM) EpiResidual epilogue in a quad-contiguous lane layout: accumulators moved by ds_bpermute, residual read / f32+bf16 writes as 64-byte quads, counted waits instead of 32 vmcnt(0) drains
# speedup vs baseline: 1.0598x; 1.0114x over previous
.LBB0_1345:
	v_lshrrev_b32_e32 v143, 2, v186
	v_and_b32_e32 v144, 3, v186
	v_and_b32_e32 v141, -16, v150
	v_add_u32_e32 v141, v141, v143
	v_lshl_add_u32 v141, s10, 8, v141
	v_and_b32_e32 v142, -13, v152
	v_lshl_or_b32 v142, v144, 2, v142
	v_lshl_or_b32 v142, s26, 8, v142
	v_lshlrev_b32_e32 v142, 2, v142
	v_lshl_add_u32 v155, v141, 12, v142
	s_lshl_b32 s80, s48, 2
	s_lshl_b32 s26, s26, 2
	s_ashr_i32 s27, s26, 31
	s_lshl_b32 s28, s26, 2
	s_add_i32 s28, s28, s80
	v_lshl_add_u32 v156, v141, 6, s28
	v_lshl_add_u32 v154, v144, 4, v143
	v_lshlrev_b32_e32 v154, 2, v154
	v_cmp_eq_u32_e64 s[28:29], 0, v144
	s_nop 7
	s_nop 7
	v_mov_b32_e32 v148, v155
	global_load_dwordx4 v[234:237], v148, s[0:1]
	global_load_dwordx4 v[238:241], v148, s[0:1] offset:64
	global_load_dwordx4 v[242:245], v148, s[0:1] offset:512
	global_load_dwordx4 v[246:249], v148, s[0:1] offset:576
	ds_bpermute_b32 v126, v154, v126
	ds_bpermute_b32 v127, v154, v127
	ds_bpermute_b32 v128, v154, v128
	ds_bpermute_b32 v129, v154, v129
	ds_bpermute_b32 v122, v154, v122
	ds_bpermute_b32 v123, v154, v123
	ds_bpermute_b32 v124, v154, v124
	ds_bpermute_b32 v125, v154, v125
	ds_bpermute_b32 v118, v154, v118
	ds_bpermute_b32 v119, v154, v119
	ds_bpermute_b32 v120, v154, v120
	ds_bpermute_b32 v121, v154, v121
	ds_bpermute_b32 v114, v154, v114
	ds_bpermute_b32 v115, v154, v115
	ds_bpermute_b32 v116, v154, v116
	ds_bpermute_b32 v117, v154, v117
	s_waitcnt vmcnt(0) lgkmcnt(0)
	v_add_f32_e32 v126, v126, v234
	v_add_f32_e32 v127, v127, v235
	v_add_f32_e32 v128, v128, v236
	v_add_f32_e32 v129, v129, v237
	v_add_f32_e32 v122, v122, v238
	v_add_f32_e32 v123, v123, v239
	v_add_f32_e32 v124, v124, v240
	v_add_f32_e32 v125, v125, v241
	v_add_f32_e32 v118, v118, v242
	v_add_f32_e32 v119, v119, v243
	v_add_f32_e32 v120, v120, v244
	v_add_f32_e32 v121, v121, v245
	v_add_f32_e32 v114, v114, v246
	v_add_f32_e32 v115, v115, v247
	v_add_f32_e32 v116, v116, v248
	v_add_f32_e32 v117, v117, v249
	v_add_u32_e32 v149, 0x10000, v155
	global_load_dwordx4 v[234:237], v149, s[0:1]
	global_load_dwordx4 v[238:241], v149, s[0:1] offset:64
	global_load_dwordx4 v[242:245], v149, s[0:1] offset:512
	global_load_dwordx4 v[246:249], v149, s[0:1] offset:576
	global_store_dwordx4 v148, v[126:129], s[0:1]
	global_store_dwordx4 v148, v[122:125], s[0:1] offset:64
	global_store_dwordx4 v148, v[118:121], s[0:1] offset:512
	global_store_dwordx4 v148, v[114:117], s[0:1] offset:576
	s_andn2_b64 vcc, exec, s[14:15]
	s_cbranch_vccnz .Lepi5_nob_0
	v_lshrrev_b32_e32 v140, 1, v148
	v_cvt_pk_bf16_f32 v250, v126, v127
	v_cvt_pk_bf16_f32 v251, v128, v129
	v_cvt_pk_bf16_f32 v252, v122, v123
	v_cvt_pk_bf16_f32 v253, v124, v125
	v_cvt_pk_bf16_f32 v136, v118, v119
	v_cvt_pk_bf16_f32 v137, v120, v121
	v_cvt_pk_bf16_f32 v138, v114, v115
	v_cvt_pk_bf16_f32 v139, v116, v117
	global_store_dwordx2 v140, v[250:251], s[12:13]
	global_store_dwordx2 v140, v[252:253], s[12:13] offset:32
	global_store_dwordx2 v140, v[136:137], s[12:13] offset:256
	global_store_dwordx2 v140, v[138:139], s[12:13] offset:288
.Lepi5_nob_0:
	ds_bpermute_b32 v110, v154, v110
	ds_bpermute_b32 v111, v154, v111
	ds_bpermute_b32 v112, v154, v112
	ds_bpermute_b32 v113, v154, v113
	ds_bpermute_b32 v106, v154, v106
	ds_bpermute_b32 v107, v154, v107
	ds_bpermute_b32 v108, v154, v108
	ds_bpermute_b32 v109, v154, v109
	ds_bpermute_b32 v102, v154, v102
	ds_bpermute_b32 v103, v154, v103
	ds_bpermute_b32 v104, v154, v104
	ds_bpermute_b32 v105, v154, v105
	ds_bpermute_b32 v98, v154, v98
	ds_bpermute_b32 v99, v154, v99
	ds_bpermute_b32 v100, v154, v100
	ds_bpermute_b32 v101, v154, v101
	v_mul_f32_e32 v157, v126, v126
	v_fmac_f32_e32 v157, v127, v127
	v_fmac_f32_e32 v157, v128, v128
	v_fmac_f32_e32 v157, v129, v129
	v_fmac_f32_e32 v157, v122, v122
	v_fmac_f32_e32 v157, v123, v123
	v_fmac_f32_e32 v157, v124, v124
	v_fmac_f32_e32 v157, v125, v125
	v_fmac_f32_e32 v157, v118, v118
	v_fmac_f32_e32 v157, v119, v119
	v_fmac_f32_e32 v157, v120, v120
	v_fmac_f32_e32 v157, v121, v121
	v_fmac_f32_e32 v157, v114, v114
	v_fmac_f32_e32 v157, v115, v115
	v_fmac_f32_e32 v157, v116, v116
	v_fmac_f32_e32 v157, v117, v117
	s_nop 1
	v_add_f32_dpp v157, v157, v157 quad_perm:[1,0,3,2] row_mask:0xf bank_mask:0xf
	s_nop 1
	v_add_f32_dpp v157, v157, v157 quad_perm:[2,3,0,1] row_mask:0xf bank_mask:0xf
	s_and_saveexec_b64 s[10:11], s[28:29]
	global_store_dword v156, v157, s[2:3]
	s_or_b64 exec, exec, s[10:11]
	s_waitcnt vmcnt(5) lgkmcnt(0)
	v_add_f32_e32 v110, v110, v234
	v_add_f32_e32 v111, v111, v235
	v_add_f32_e32 v112, v112, v236
	v_add_f32_e32 v113, v113, v237
	v_add_f32_e32 v106, v106, v238
	v_add_f32_e32 v107, v107, v239
	v_add_f32_e32 v108, v108, v240
	v_add_f32_e32 v109, v109, v241
	v_add_f32_e32 v102, v102, v242
	v_add_f32_e32 v103, v103, v243
	v_add_f32_e32 v104, v104, v244
	v_add_f32_e32 v105, v105, v245
	v_add_f32_e32 v98, v98, v246
	v_add_f32_e32 v99, v99, v247
	v_add_f32_e32 v100, v100, v248
	v_add_f32_e32 v101, v101, v249
	v_add_u32_e32 v148, 0x20000, v155
	global_load_dwordx4 v[234:237], v148, s[0:1]
	global_load_dwordx4 v[238:241], v148, s[0:1] offset:64
	global_load_dwordx4 v[242:245], v148, s[0:1] offset:512
	global_load_dwordx4 v[246:249], v148, s[0:1] offset:576
	global_store_dwordx4 v149, v[110:113], s[0:1]
	global_store_dwordx4 v149, v[106:109], s[0:1] offset:64
	global_store_dwordx4 v149, v[102:105], s[0:1] offset:512
	global_store_dwordx4 v149, v[98:101], s[0:1] offset:576
	s_andn2_b64 vcc, exec, s[14:15]
	s_cbranch_vccnz .Lepi5_nob_1
	v_lshrrev_b32_e32 v140, 1, v149
	v_cvt_pk_bf16_f32 v250, v110, v111
	v_cvt_pk_bf16_f32 v251, v112, v113
	v_cvt_pk_bf16_f32 v252, v106, v107
	v_cvt_pk_bf16_f32 v253, v108, v109
	v_cvt_pk_bf16_f32 v136, v102, v103
	v_cvt_pk_bf16_f32 v137, v104, v105
	v_cvt_pk_bf16_f32 v138, v98, v99
	v_cvt_pk_bf16_f32 v139, v100, v101
	global_store_dwordx2 v140, v[250:251], s[12:13]
	global_store_dwordx2 v140, v[252:253], s[12:13] offset:32
	global_store_dwordx2 v140, v[136:137], s[12:13] offset:256
	global_store_dwordx2 v140, v[138:139], s[12:13] offset:288
.Lepi5_nob_1:
	ds_bpermute_b32 v94, v154, v94
	ds_bpermute_b32 v95, v154, v95
	ds_bpermute_b32 v96, v154, v96
	ds_bpermute_b32 v97, v154, v97
	ds_bpermute_b32 v90, v154, v90
	ds_bpermute_b32 v91, v154, v91
	ds_bpermute_b32 v92, v154, v92
	ds_bpermute_b32 v93, v154, v93
	ds_bpermute_b32 v86, v154, v86
	ds_bpermute_b32 v87, v154, v87
	ds_bpermute_b32 v88, v154, v88
	ds_bpermute_b32 v89, v154, v89
	ds_bpermute_b32 v82, v154, v82
	ds_bpermute_b32 v83, v154, v83
	ds_bpermute_b32 v84, v154, v84
	ds_bpermute_b32 v85, v154, v85
	v_mul_f32_e32 v157, v110, v110
	v_fmac_f32_e32 v157, v111, v111
	v_fmac_f32_e32 v157, v112, v112
	v_fmac_f32_e32 v157, v113, v113
	v_fmac_f32_e32 v157, v106, v106
	v_fmac_f32_e32 v157, v107, v107
	v_fmac_f32_e32 v157, v108, v108
	v_fmac_f32_e32 v157, v109, v109
	v_fmac_f32_e32 v157, v102, v102
	v_fmac_f32_e32 v157, v103, v103
	v_fmac_f32_e32 v157, v104, v104
	v_fmac_f32_e32 v157, v105, v105
	v_fmac_f32_e32 v157, v98, v98
	v_fmac_f32_e32 v157, v99, v99
	v_fmac_f32_e32 v157, v100, v100
	v_fmac_f32_e32 v157, v101, v101
	s_nop 1
	v_add_f32_dpp v157, v157, v157 quad_perm:[1,0,3,2] row_mask:0xf bank_mask:0xf
	s_nop 1
	v_add_f32_dpp v157, v157, v157 quad_perm:[2,3,0,1] row_mask:0xf bank_mask:0xf
	s_and_saveexec_b64 s[10:11], s[28:29]
	global_store_dword v156, v157, s[2:3] offset:1024
	s_or_b64 exec, exec, s[10:11]
	s_waitcnt vmcnt(5) lgkmcnt(0)
	v_add_f32_e32 v94, v94, v234
	v_add_f32_e32 v95, v95, v235
	v_add_f32_e32 v96, v96, v236
	v_add_f32_e32 v97, v97, v237
	v_add_f32_e32 v90, v90, v238
	v_add_f32_e32 v91, v91, v239
	v_add_f32_e32 v92, v92, v240
	v_add_f32_e32 v93, v93, v241
	v_add_f32_e32 v86, v86, v242
	v_add_f32_e32 v87, v87, v243
	v_add_f32_e32 v88, v88, v244
	v_add_f32_e32 v89, v89, v245
	v_add_f32_e32 v82, v82, v246
	v_add_f32_e32 v83, v83, v247
	v_add_f32_e32 v84, v84, v248
	v_add_f32_e32 v85, v85, v249
	v_add_u32_e32 v149, 0x30000, v155
	global_load_dwordx4 v[234:237], v149, s[0:1]
	global_load_dwordx4 v[238:241], v149, s[0:1] offset:64
	global_load_dwordx4 v[242:245], v149, s[0:1] offset:512
	global_load_dwordx4 v[246:249], v149, s[0:1] offset:576
	global_store_dwordx4 v148, v[94:97], s[0:1]
	global_store_dwordx4 v148, v[90:93], s[0:1] offset:64
	global_store_dwordx4 v148, v[86:89], s[0:1] offset:512
	global_store_dwordx4 v148, v[82:85], s[0:1] offset:576
	s_andn2_b64 vcc, exec, s[14:15]
	s_cbranch_vccnz .Lepi5_nob_2
	v_lshrrev_b32_e32 v140, 1, v148
	v_cvt_pk_bf16_f32 v250, v94, v95
	v_cvt_pk_bf16_f32 v251, v96, v97
	v_cvt_pk_bf16_f32 v252, v90, v91
	v_cvt_pk_bf16_f32 v253, v92, v93
	v_cvt_pk_bf16_f32 v136, v86, v87
	v_cvt_pk_bf16_f32 v137, v88, v89
	v_cvt_pk_bf16_f32 v138, v82, v83
	v_cvt_pk_bf16_f32 v139, v84, v85
	global_store_dwordx2 v140, v[250:251], s[12:13]
	global_store_dwordx2 v140, v[252:253], s[12:13] offset:32
	global_store_dwordx2 v140, v[136:137], s[12:13] offset:256
	global_store_dwordx2 v140, v[138:139], s[12:13] offset:288
.Lepi5_nob_2:
	ds_bpermute_b32 v78, v154, v78
	ds_bpermute_b32 v79, v154, v79
	ds_bpermute_b32 v80, v154, v80
	ds_bpermute_b32 v81, v154, v81
	ds_bpermute_b32 v74, v154, v74
	ds_bpermute_b32 v75, v154, v75
	ds_bpermute_b32 v76, v154, v76
	ds_bpermute_b32 v77, v154, v77
	ds_bpermute_b32 v70, v154, v70
	ds_bpermute_b32 v71, v154, v71
	ds_bpermute_b32 v72, v154, v72
	ds_bpermute_b32 v73, v154, v73
	ds_bpermute_b32 v66, v154, v66
	ds_bpermute_b32 v67, v154, v67
	ds_bpermute_b32 v68, v154, v68
	ds_bpermute_b32 v69, v154, v69
	v_mul_f32_e32 v157, v94, v94
	v_fmac_f32_e32 v157, v95, v95
	v_fmac_f32_e32 v157, v96, v96
	v_fmac_f32_e32 v157, v97, v97
	v_fmac_f32_e32 v157, v90, v90
	v_fmac_f32_e32 v157, v91, v91
	v_fmac_f32_e32 v157, v92, v92
	v_fmac_f32_e32 v157, v93, v93
	v_fmac_f32_e32 v157, v86, v86
	v_fmac_f32_e32 v157, v87, v87
	v_fmac_f32_e32 v157, v88, v88
	v_fmac_f32_e32 v157, v89, v89
	v_fmac_f32_e32 v157, v82, v82
	v_fmac_f32_e32 v157, v83, v83
	v_fmac_f32_e32 v157, v84, v84
	v_fmac_f32_e32 v157, v85, v85
	s_nop 1
	v_add_f32_dpp v157, v157, v157 quad_perm:[1,0,3,2] row_mask:0xf bank_mask:0xf
	s_nop 1
	v_add_f32_dpp v157, v157, v157 quad_perm:[2,3,0,1] row_mask:0xf bank_mask:0xf
	s_and_saveexec_b64 s[10:11], s[28:29]
	global_store_dword v156, v157, s[2:3] offset:2048
	s_or_b64 exec, exec, s[10:11]
	s_waitcnt vmcnt(5) lgkmcnt(0)
	v_add_f32_e32 v78, v78, v234
	v_add_f32_e32 v79, v79, v235
	v_add_f32_e32 v80, v80, v236
	v_add_f32_e32 v81, v81, v237
	v_add_f32_e32 v74, v74, v238
	v_add_f32_e32 v75, v75, v239
	v_add_f32_e32 v76, v76, v240
	v_add_f32_e32 v77, v77, v241
	v_add_f32_e32 v70, v70, v242
	v_add_f32_e32 v71, v71, v243
	v_add_f32_e32 v72, v72, v244
	v_add_f32_e32 v73, v73, v245
	v_add_f32_e32 v66, v66, v246
	v_add_f32_e32 v67, v67, v247
	v_add_f32_e32 v68, v68, v248
	v_add_f32_e32 v69, v69, v249
	v_add_u32_e32 v148, 0x80000, v155
	global_load_dwordx4 v[234:237], v148, s[0:1]
	global_load_dwordx4 v[238:241], v148, s[0:1] offset:64
	global_load_dwordx4 v[242:245], v148, s[0:1] offset:512
	global_load_dwordx4 v[246:249], v148, s[0:1] offset:576
	global_store_dwordx4 v149, v[78:81], s[0:1]
	global_store_dwordx4 v149, v[74:77], s[0:1] offset:64
	global_store_dwordx4 v149, v[70:73], s[0:1] offset:512
	global_store_dwordx4 v149, v[66:69], s[0:1] offset:576
	s_andn2_b64 vcc, exec, s[14:15]
	s_cbranch_vccnz .Lepi5_nob_3
	v_lshrrev_b32_e32 v140, 1, v149
	v_cvt_pk_bf16_f32 v250, v78, v79
	v_cvt_pk_bf16_f32 v251, v80, v81
	v_cvt_pk_bf16_f32 v252, v74, v75
	v_cvt_pk_bf16_f32 v253, v76, v77
	v_cvt_pk_bf16_f32 v136, v70, v71
	v_cvt_pk_bf16_f32 v137, v72, v73
	v_cvt_pk_bf16_f32 v138, v66, v67
	v_cvt_pk_bf16_f32 v139, v68, v69
	global_store_dwordx2 v140, v[250:251], s[12:13]
	global_store_dwordx2 v140, v[252:253], s[12:13] offset:32
	global_store_dwordx2 v140, v[136:137], s[12:13] offset:256
	global_store_dwordx2 v140, v[138:139], s[12:13] offset:288
.Lepi5_nob_3:
	ds_bpermute_b32 v62, v154, v62
	ds_bpermute_b32 v63, v154, v63
	ds_bpermute_b32 v64, v154, v64
	ds_bpermute_b32 v65, v154, v65
	ds_bpermute_b32 v58, v154, v58
	ds_bpermute_b32 v59, v154, v59
	ds_bpermute_b32 v60, v154, v60
	ds_bpermute_b32 v61, v154, v61
	ds_bpermute_b32 v54, v154, v54
	ds_bpermute_b32 v55, v154, v55
	ds_bpermute_b32 v56, v154, v56
	ds_bpermute_b32 v57, v154, v57
	ds_bpermute_b32 v50, v154, v50
	ds_bpermute_b32 v51, v154, v51
	ds_bpermute_b32 v52, v154, v52
	ds_bpermute_b32 v53, v154, v53
	v_mul_f32_e32 v157, v78, v78
	v_fmac_f32_e32 v157, v79, v79
	v_fmac_f32_e32 v157, v80, v80
	v_fmac_f32_e32 v157, v81, v81
	v_fmac_f32_e32 v157, v74, v74
	v_fmac_f32_e32 v157, v75, v75
	v_fmac_f32_e32 v157, v76, v76
	v_fmac_f32_e32 v157, v77, v77
	v_fmac_f32_e32 v157, v70, v70
	v_fmac_f32_e32 v157, v71, v71
	v_fmac_f32_e32 v157, v72, v72
	v_fmac_f32_e32 v157, v73, v73
	v_fmac_f32_e32 v157, v66, v66
	v_fmac_f32_e32 v157, v67, v67
	v_fmac_f32_e32 v157, v68, v68
	v_fmac_f32_e32 v157, v69, v69
	s_nop 1
	v_add_f32_dpp v157, v157, v157 quad_perm:[1,0,3,2] row_mask:0xf bank_mask:0xf
	s_nop 1
	v_add_f32_dpp v157, v157, v157 quad_perm:[2,3,0,1] row_mask:0xf bank_mask:0xf
	s_and_saveexec_b64 s[10:11], s[28:29]
	global_store_dword v156, v157, s[2:3] offset:3072
	s_or_b64 exec, exec, s[10:11]
	s_waitcnt vmcnt(5) lgkmcnt(0)
	v_add_f32_e32 v62, v62, v234
	v_add_f32_e32 v63, v63, v235
	v_add_f32_e32 v64, v64, v236
	v_add_f32_e32 v65, v65, v237
	v_add_f32_e32 v58, v58, v238
	v_add_f32_e32 v59, v59, v239
	v_add_f32_e32 v60, v60, v240
	v_add_f32_e32 v61, v61, v241
	v_add_f32_e32 v54, v54, v242
	v_add_f32_e32 v55, v55, v243
	v_add_f32_e32 v56, v56, v244
	v_add_f32_e32 v57, v57, v245
	v_add_f32_e32 v50, v50, v246
	v_add_f32_e32 v51, v51, v247
	v_add_f32_e32 v52, v52, v248
	v_add_f32_e32 v53, v53, v249
	v_add_u32_e32 v149, 0x90000, v155
	global_load_dwordx4 v[234:237], v149, s[0:1]
	global_load_dwordx4 v[238:241], v149, s[0:1] offset:64
	global_load_dwordx4 v[242:245], v149, s[0:1] offset:512
	global_load_dwordx4 v[246:249], v149, s[0:1] offset:576
	global_store_dwordx4 v148, v[62:65], s[0:1]
	global_store_dwordx4 v148, v[58:61], s[0:1] offset:64
	global_store_dwordx4 v148, v[54:57], s[0:1] offset:512
	global_store_dwordx4 v148, v[50:53], s[0:1] offset:576
	s_andn2_b64 vcc, exec, s[14:15]
	s_cbranch_vccnz .Lepi5_nob_4
	v_lshrrev_b32_e32 v140, 1, v148
	v_cvt_pk_bf16_f32 v250, v62, v63
	v_cvt_pk_bf16_f32 v251, v64, v65
	v_cvt_pk_bf16_f32 v252, v58, v59
	v_cvt_pk_bf16_f32 v253, v60, v61
	v_cvt_pk_bf16_f32 v136, v54, v55
	v_cvt_pk_bf16_f32 v137, v56, v57
	v_cvt_pk_bf16_f32 v138, v50, v51
	v_cvt_pk_bf16_f32 v139, v52, v53
	global_store_dwordx2 v140, v[250:251], s[12:13]
	global_store_dwordx2 v140, v[252:253], s[12:13] offset:32
	global_store_dwordx2 v140, v[136:137], s[12:13] offset:256
	global_store_dwordx2 v140, v[138:139], s[12:13] offset:288
.Lepi5_nob_4:
	ds_bpermute_b32 v46, v154, v46
	ds_bpermute_b32 v47, v154, v47
	ds_bpermute_b32 v48, v154, v48
	ds_bpermute_b32 v49, v154, v49
	ds_bpermute_b32 v42, v154, v42
	ds_bpermute_b32 v43, v154, v43
	ds_bpermute_b32 v44, v154, v44
	ds_bpermute_b32 v45, v154, v45
	ds_bpermute_b32 v38, v154, v38
	ds_bpermute_b32 v39, v154, v39
	ds_bpermute_b32 v40, v154, v40
	ds_bpermute_b32 v41, v154, v41
	ds_bpermute_b32 v34, v154, v34
	ds_bpermute_b32 v35, v154, v35
	ds_bpermute_b32 v36, v154, v36
	ds_bpermute_b32 v37, v154, v37
	v_mul_f32_e32 v157, v62, v62
	v_fmac_f32_e32 v157, v63, v63
	v_fmac_f32_e32 v157, v64, v64
	v_fmac_f32_e32 v157, v65, v65
	v_fmac_f32_e32 v157, v58, v58
	v_fmac_f32_e32 v157, v59, v59
	v_fmac_f32_e32 v157, v60, v60
	v_fmac_f32_e32 v157, v61, v61
	v_fmac_f32_e32 v157, v54, v54
	v_fmac_f32_e32 v157, v55, v55
	v_fmac_f32_e32 v157, v56, v56
	v_fmac_f32_e32 v157, v57, v57
	v_fmac_f32_e32 v157, v50, v50
	v_fmac_f32_e32 v157, v51, v51
	v_fmac_f32_e32 v157, v52, v52
	v_fmac_f32_e32 v157, v53, v53
	s_nop 1
	v_add_f32_dpp v157, v157, v157 quad_perm:[1,0,3,2] row_mask:0xf bank_mask:0xf
	s_nop 1
	v_add_f32_dpp v157, v157, v157 quad_perm:[2,3,0,1] row_mask:0xf bank_mask:0xf
	v_add_u32_e32 v141, 0x2000, v156
	s_and_saveexec_b64 s[10:11], s[28:29]
	global_store_dword v141, v157, s[2:3]
	s_or_b64 exec, exec, s[10:11]
	s_waitcnt vmcnt(5) lgkmcnt(0)
	v_add_f32_e32 v46, v46, v234
	v_add_f32_e32 v47, v47, v235
	v_add_f32_e32 v48, v48, v236
	v_add_f32_e32 v49, v49, v237
	v_add_f32_e32 v42, v42, v238
	v_add_f32_e32 v43, v43, v239
	v_add_f32_e32 v44, v44, v240
	v_add_f32_e32 v45, v45, v241
	v_add_f32_e32 v38, v38, v242
	v_add_f32_e32 v39, v39, v243
	v_add_f32_e32 v40, v40, v244
	v_add_f32_e32 v41, v41, v245
	v_add_f32_e32 v34, v34, v246
	v_add_f32_e32 v35, v35, v247
	v_add_f32_e32 v36, v36, v248
	v_add_f32_e32 v37, v37, v249
	v_add_u32_e32 v148, 0xa0000, v155
	global_load_dwordx4 v[234:237], v148, s[0:1]
	global_load_dwordx4 v[238:241], v148, s[0:1] offset:64
	global_load_dwordx4 v[242:245], v148, s[0:1] offset:512
	global_load_dwordx4 v[246:249], v148, s[0:1] offset:576
	global_store_dwordx4 v149, v[46:49], s[0:1]
	global_store_dwordx4 v149, v[42:45], s[0:1] offset:64
	global_store_dwordx4 v149, v[38:41], s[0:1] offset:512
	global_store_dwordx4 v149, v[34:37], s[0:1] offset:576
	s_andn2_b64 vcc, exec, s[14:15]
	s_cbranch_vccnz .Lepi5_nob_5
	v_lshrrev_b32_e32 v140, 1, v149
	v_cvt_pk_bf16_f32 v250, v46, v47
	v_cvt_pk_bf16_f32 v251, v48, v49
	v_cvt_pk_bf16_f32 v252, v42, v43
	v_cvt_pk_bf16_f32 v253, v44, v45
	v_cvt_pk_bf16_f32 v136, v38, v39
	v_cvt_pk_bf16_f32 v137, v40, v41
	v_cvt_pk_bf16_f32 v138, v34, v35
	v_cvt_pk_bf16_f32 v139, v36, v37
	global_store_dwordx2 v140, v[250:251], s[12:13]
	global_store_dwordx2 v140, v[252:253], s[12:13] offset:32
	global_store_dwordx2 v140, v[136:137], s[12:13] offset:256
	global_store_dwordx2 v140, v[138:139], s[12:13] offset:288
.Lepi5_nob_5:
	ds_bpermute_b32 v30, v154, v30
	ds_bpermute_b32 v31, v154, v31
	ds_bpermute_b32 v32, v154, v32
	ds_bpermute_b32 v33, v154, v33
	ds_bpermute_b32 v26, v154, v26
	ds_bpermute_b32 v27, v154, v27
	ds_bpermute_b32 v28, v154, v28
	ds_bpermute_b32 v29, v154, v29
	ds_bpermute_b32 v22, v154, v22
	ds_bpermute_b32 v23, v154, v23
	ds_bpermute_b32 v24, v154, v24
	ds_bpermute_b32 v25, v154, v25
	ds_bpermute_b32 v18, v154, v18
	ds_bpermute_b32 v19, v154, v19
	ds_bpermute_b32 v20, v154, v20
	ds_bpermute_b32 v21, v154, v21
	v_mul_f32_e32 v157, v46, v46
	v_fmac_f32_e32 v157, v47, v47
	v_fmac_f32_e32 v157, v48, v48
	v_fmac_f32_e32 v157, v49, v49
	v_fmac_f32_e32 v157, v42, v42
	v_fmac_f32_e32 v157, v43, v43
	v_fmac_f32_e32 v157, v44, v44
	v_fmac_f32_e32 v157, v45, v45
	v_fmac_f32_e32 v157, v38, v38
	v_fmac_f32_e32 v157, v39, v39
	v_fmac_f32_e32 v157, v40, v40
	v_fmac_f32_e32 v157, v41, v41
	v_fmac_f32_e32 v157, v34, v34
	v_fmac_f32_e32 v157, v35, v35
	v_fmac_f32_e32 v157, v36, v36
	v_fmac_f32_e32 v157, v37, v37
	s_nop 1
	v_add_f32_dpp v157, v157, v157 quad_perm:[1,0,3,2] row_mask:0xf bank_mask:0xf
	s_nop 1
	v_add_f32_dpp v157, v157, v157 quad_perm:[2,3,0,1] row_mask:0xf bank_mask:0xf
	v_add_u32_e32 v141, 0x2000, v156
	s_and_saveexec_b64 s[10:11], s[28:29]
	global_store_dword v141, v157, s[2:3] offset:1024
	s_or_b64 exec, exec, s[10:11]
	s_waitcnt vmcnt(5) lgkmcnt(0)
	v_add_f32_e32 v30, v30, v234
	v_add_f32_e32 v31, v31, v235
	v_add_f32_e32 v32, v32, v236
	v_add_f32_e32 v33, v33, v237
	v_add_f32_e32 v26, v26, v238
	v_add_f32_e32 v27, v27, v239
	v_add_f32_e32 v28, v28, v240
	v_add_f32_e32 v29, v29, v241
	v_add_f32_e32 v22, v22, v242
	v_add_f32_e32 v23, v23, v243
	v_add_f32_e32 v24, v24, v244
	v_add_f32_e32 v25, v25, v245
	v_add_f32_e32 v18, v18, v246
	v_add_f32_e32 v19, v19, v247
	v_add_f32_e32 v20, v20, v248
	v_add_f32_e32 v21, v21, v249
	v_add_u32_e32 v149, 0xb0000, v155
	global_load_dwordx4 v[234:237], v149, s[0:1]
	global_load_dwordx4 v[238:241], v149, s[0:1] offset:64
	global_load_dwordx4 v[242:245], v149, s[0:1] offset:512
	global_load_dwordx4 v[246:249], v149, s[0:1] offset:576
	global_store_dwordx4 v148, v[30:33], s[0:1]
	global_store_dwordx4 v148, v[26:29], s[0:1] offset:64
	global_store_dwordx4 v148, v[22:25], s[0:1] offset:512
	global_store_dwordx4 v148, v[18:21], s[0:1] offset:576
	s_andn2_b64 vcc, exec, s[14:15]
	s_cbranch_vccnz .Lepi5_nob_6
	v_lshrrev_b32_e32 v140, 1, v148
	v_cvt_pk_bf16_f32 v250, v30, v31
	v_cvt_pk_bf16_f32 v251, v32, v33
	v_cvt_pk_bf16_f32 v252, v26, v27
	v_cvt_pk_bf16_f32 v253, v28, v29
	v_cvt_pk_bf16_f32 v136, v22, v23
	v_cvt_pk_bf16_f32 v137, v24, v25
	v_cvt_pk_bf16_f32 v138, v18, v19
	v_cvt_pk_bf16_f32 v139, v20, v21
	global_store_dwordx2 v140, v[250:251], s[12:13]
	global_store_dwordx2 v140, v[252:253], s[12:13] offset:32
	global_store_dwordx2 v140, v[136:137], s[12:13] offset:256
	global_store_dwordx2 v140, v[138:139], s[12:13] offset:288
.Lepi5_nob_6:
	ds_bpermute_b32 v14, v154, v14
	ds_bpermute_b32 v15, v154, v15
	ds_bpermute_b32 v16, v154, v16
	ds_bpermute_b32 v17, v154, v17
	ds_bpermute_b32 v10, v154, v10
	ds_bpermute_b32 v11, v154, v11
	ds_bpermute_b32 v12, v154, v12
	ds_bpermute_b32 v13, v154, v13
	ds_bpermute_b32 v6, v154, v6
	ds_bpermute_b32 v7, v154, v7
	ds_bpermute_b32 v8, v154, v8
	ds_bpermute_b32 v9, v154, v9
	ds_bpermute_b32 v2, v154, v2
	ds_bpermute_b32 v3, v154, v3
	ds_bpermute_b32 v4, v154, v4
	ds_bpermute_b32 v5, v154, v5
	v_mul_f32_e32 v157, v30, v30
	v_fmac_f32_e32 v157, v31, v31
	v_fmac_f32_e32 v157, v32, v32
	v_fmac_f32_e32 v157, v33, v33
	v_fmac_f32_e32 v157, v26, v26
	v_fmac_f32_e32 v157, v27, v27
	v_fmac_f32_e32 v157, v28, v28
	v_fmac_f32_e32 v157, v29, v29
	v_fmac_f32_e32 v157, v22, v22
	v_fmac_f32_e32 v157, v23, v23
	v_fmac_f32_e32 v157, v24, v24
	v_fmac_f32_e32 v157, v25, v25
	v_fmac_f32_e32 v157, v18, v18
	v_fmac_f32_e32 v157, v19, v19
	v_fmac_f32_e32 v157, v20, v20
	v_fmac_f32_e32 v157, v21, v21
	s_nop 1
	v_add_f32_dpp v157, v157, v157 quad_perm:[1,0,3,2] row_mask:0xf bank_mask:0xf
	s_nop 1
	v_add_f32_dpp v157, v157, v157 quad_perm:[2,3,0,1] row_mask:0xf bank_mask:0xf
	v_add_u32_e32 v141, 0x2000, v156
	s_and_saveexec_b64 s[10:11], s[28:29]
	global_store_dword v141, v157, s[2:3] offset:2048
	s_or_b64 exec, exec, s[10:11]
	s_waitcnt vmcnt(5) lgkmcnt(0)
	v_add_f32_e32 v14, v14, v234
	v_add_f32_e32 v15, v15, v235
	v_add_f32_e32 v16, v16, v236
	v_add_f32_e32 v17, v17, v237
	v_add_f32_e32 v10, v10, v238
	v_add_f32_e32 v11, v11, v239
	v_add_f32_e32 v12, v12, v240
	v_add_f32_e32 v13, v13, v241
	v_add_f32_e32 v6, v6, v242
	v_add_f32_e32 v7, v7, v243
	v_add_f32_e32 v8, v8, v244
	v_add_f32_e32 v9, v9, v245
	v_add_f32_e32 v2, v2, v246
	v_add_f32_e32 v3, v3, v247
	v_add_f32_e32 v4, v4, v248
	v_add_f32_e32 v5, v5, v249
	global_store_dwordx4 v149, v[14:17], s[0:1]
	global_store_dwordx4 v149, v[10:13], s[0:1] offset:64
	global_store_dwordx4 v149, v[6:9], s[0:1] offset:512
	global_store_dwordx4 v149, v[2:5], s[0:1] offset:576
	s_andn2_b64 vcc, exec, s[14:15]
	s_cbranch_vccnz .Lepi5_nob_7
	v_lshrrev_b32_e32 v140, 1, v149
	v_cvt_pk_bf16_f32 v250, v14, v15
	v_cvt_pk_bf16_f32 v251, v16, v17
	v_cvt_pk_bf16_f32 v252, v10, v11
	v_cvt_pk_bf16_f32 v253, v12, v13
	v_cvt_pk_bf16_f32 v136, v6, v7
	v_cvt_pk_bf16_f32 v137, v8, v9
	v_cvt_pk_bf16_f32 v138, v2, v3
	v_cvt_pk_bf16_f32 v139, v4, v5
	global_store_dwordx2 v140, v[250:251], s[12:13]
	global_store_dwordx2 v140, v[252:253], s[12:13] offset:32
	global_store_dwordx2 v140, v[136:137], s[12:13] offset:256
	global_store_dwordx2 v140, v[138:139], s[12:13] offset:288
.Lepi5_nob_7:
	v_mul_f32_e32 v157, v14, v14
	v_fmac_f32_e32 v157, v15, v15
	v_fmac_f32_e32 v157, v16, v16
	v_fmac_f32_e32 v157, v17, v17
	v_fmac_f32_e32 v157, v10, v10
	v_fmac_f32_e32 v157, v11, v11
	v_fmac_f32_e32 v157, v12, v12
	v_fmac_f32_e32 v157, v13, v13
	v_fmac_f32_e32 v157, v6, v6
	v_fmac_f32_e32 v157, v7, v7
	v_fmac_f32_e32 v157, v8, v8
	v_fmac_f32_e32 v157, v9, v9
	v_fmac_f32_e32 v157, v2, v2
	v_fmac_f32_e32 v157, v3, v3
	v_fmac_f32_e32 v157, v4, v4
	v_fmac_f32_e32 v157, v5, v5
	s_nop 1
	v_add_f32_dpp v157, v157, v157 quad_perm:[1,0,3,2] row_mask:0xf bank_mask:0xf
	s_nop 1
	v_add_f32_dpp v157, v157, v157 quad_perm:[2,3,0,1] row_mask:0xf bank_mask:0xf
	v_add_u32_e32 v141, 0x2000, v156
	s_and_saveexec_b64 s[10:11], s[28:29]
	global_store_dword v141, v157, s[2:3] offset:3072
	s_or_b64 exec, exec, s[10:11]
.LBB0_1425:
	s_andn2_b64 vcc, exec, s[8:9]
	s_mov_b64 s[8:9], -1
	s_cbranch_vccnz .LBB0_1334
	s_andn2_b64 vcc, exec, s[4:5]
	s_cbranch_vccnz .LBB0_1333
	s_barrier
	s_branch .LBB0_1333
